# out-proj residual epilogue: all 16 stream loads hoisted to epilogue start (both EpiRes instances)
# speedup vs baseline: 1.0010x; 1.0010x over previous
; #define PG8_STAGE(bufoff, gbase, voff) do { _Pragma("unroll") for (int _i = 0; _i < 2; ++_i) glds16_s((gbase), (voff)[_i], ldsb + (unsigned)((bufoff) + _i * 8192)); } while (0)
; #define PG8_LDA(dst, b, h) do { _Pragma("unroll") for (int m = 0; m < 4; ++m) _Pragma("unroll") for (int k = 0; k < 2; ++k) dst[m][k] = *(const LAS h16x8*)(lds + PG8_SA(b, h) + aoff + m * 2048 + k * 1024); } while (0)
; #define PG8_LDB(dst, b, h) do { _Pragma("unroll") for (int n = 0; n < 2; ++n) _Pragma("unroll") for (int k = 0; k < 2; ++k) dst[n][k] = *(const LAS h16x8*)(lds + PG8_SB(b, h) + boff + n * 2048 + k * 1024); } while (0)
; #define PG8_MMA(ai, bj, At, Bt) do { __builtin_amdgcn_s_setprio(1); _Pragma("unroll") for (int m = 0; m < 4; ++m) _Pragma("unroll") for (int n = 0; n < 2; ++n) _Pragma("unroll") for (int k = 0; k < 2; ++k) \
;         acc[ai][bj][m][n] = mma_step<I8>(Bt[n][k], At[m][k], acc[ai][bj][m][n]); __builtin_amdgcn_s_setprio(0); } while (0)
; #define PG8_WAIT_V(n) asm volatile("s_waitcnt vmcnt(" #n ")" ::: "memory")
; #define PG8_WAIT_L(n) asm volatile("s_waitcnt lgkmcnt(" #n ")" ::: "memory")
; #define PG8_BAR __builtin_amdgcn_s_barrier()
; #define PG8_SCHED __builtin_amdgcn_sched_barrier(0)
; template <class Prob, class Epi, bool I8 = false, bool ALIGN_EPI = true, bool SP2 = true>
; __device__ __forceinline__ void gemm_phase(LAS unsigned char* lds, int wave, const Prob& P, const Epi& E) {
;     ...
;         for (int t = 0; t < nt; t += 2) {
;             const bool last = (t == nt - 2);
;             const char* a1 = cA + (size_t)(t + 1) * kstep;
;             const char* a2 = last ? nA : cA + (size_t)(t + 2) * kstep; const char* b2 = last ? nB : cB + (size_t)(t + 2) * kstep;
;             const char* a3 = a2 + kstep; const char* b3 = b2 + kstep;
;             if constexpr (SP2) {
;             PG8_LDB(B0, 0, 0); PG8_LDB(B1, 0, 1); PG8_SCHED; PG8_LDA(At, 0, 0); PG8_STAGE(PG8_SA(1, 1), a1 + hstepA, voffA);
;             PG8_WAIT_V(8); PG8_WAIT_L(0); PG8_BAR; PG8_MMA(0, 0, At, B0); PG8_MMA(0, 1, At, B1); PG8_BAR; PG8_SCHED;
;             PG8_LDA(At, 0, 1); PG8_STAGE(PG8_SB(0, 0), b2, voffB); PG8_STAGE(PG8_SB(0, 1), b2 + hstepB, voffB); PG8_STAGE(PG8_SA(0, 0), a2, voffA);
;             PG8_WAIT_V(8); PG8_WAIT_L(0); PG8_BAR; PG8_MMA(1, 0, At, B0); PG8_MMA(1, 1, At, B1); PG8_BAR; PG8_SCHED;
.LBB0_464:
	v_add_u32_e32 v140, 0x10000, v146
	ds_read_b128 v[128:131], v140
	ds_read_b128 v[132:135], v140 offset:1024
	ds_read_b128 v[136:139], v140 offset:2048
	ds_read_b128 v[148:151], v140 offset:3072
	v_add_u32_e32 v140, 0x14000, v146
	ds_read_b128 v[152:155], v140
	ds_read_b128 v[156:159], v140 offset:1024
	ds_read_b128 v[160:163], v140 offset:2048
	ds_read_b128 v[164:167], v140 offset:3072
	s_cmp_eq_u32 s1, 28
	s_cselect_b32 s48, s83, s85
	s_cselect_b32 s49, s27, s86
	s_cselect_b32 s46, s84, s87
	s_cselect_b32 s47, s23, s0
	s_add_u32 s44, s48, 0x80
	s_addc_u32 s45, s49, 0
	ds_read_b128 v[168:171], v147
	ds_read_b128 v[172:175], v147 offset:1024
	ds_read_b128 v[176:179], v147 offset:2048
	ds_read_b128 v[180:183], v147 offset:3072
	ds_read_b128 v[184:187], v147 offset:4096
	ds_read_b128 v[188:191], v147 offset:5120
	ds_read_b128 v[192:195], v147 offset:6144
	ds_read_b128 v[196:199], v147 offset:7168
	s_mov_b32 s4, m0
	s_mov_b32 m0, s77
	s_nop 0
	global_load_lds_dwordx4 v142, s[40:41]
	s_mov_b32 m0, s4
	s_nop 0
	s_mov_b32 s4, m0
	s_mov_b32 m0, s79
	s_nop 0
	global_load_lds_dwordx4 v144, s[40:41]
	s_mov_b32 m0, s4
	s_waitcnt vmcnt(8)
	s_waitcnt lgkmcnt(0)
	s_barrier
	s_setprio 1
	s_waitcnt lgkmcnt(7)
	v_mfma_f32_16x16x32_f16 v[124:127], v[128:131], v[168:171], v[124:127]
	v_mfma_f32_16x16x32_f16 v[120:123], v[136:139], v[168:171], v[120:123]
	s_waitcnt lgkmcnt(5)
	v_mfma_f32_16x16x32_f16 v[116:119], v[128:131], v[176:179], v[116:119]
	v_mfma_f32_16x16x32_f16 v[112:115], v[136:139], v[176:179], v[112:115]
	s_waitcnt lgkmcnt(3)
	v_mfma_f32_16x16x32_f16 v[108:111], v[128:131], v[184:187], v[108:111]
	v_mfma_f32_16x16x32_f16 v[104:107], v[136:139], v[184:187], v[104:107]
	s_waitcnt lgkmcnt(1)
	v_mfma_f32_16x16x32_f16 v[100:103], v[128:131], v[192:195], v[100:103]
	v_mfma_f32_16x16x32_f16 v[96:99], v[136:139], v[192:195], v[96:99]
	v_mfma_f32_16x16x32_f16 v[124:127], v[132:135], v[172:175], v[124:127]
	v_mfma_f32_16x16x32_f16 v[120:123], v[148:151], v[172:175], v[120:123]
	v_mfma_f32_16x16x32_f16 v[116:119], v[132:135], v[180:183], v[116:119]
	v_mfma_f32_16x16x32_f16 v[112:115], v[148:151], v[180:183], v[112:115]
	v_mfma_f32_16x16x32_f16 v[108:111], v[132:135], v[188:191], v[108:111]
	v_mfma_f32_16x16x32_f16 v[104:107], v[148:151], v[188:191], v[104:107]
	s_waitcnt lgkmcnt(0)
	v_mfma_f32_16x16x32_f16 v[100:103], v[132:135], v[196:199], v[100:103]
	v_mfma_f32_16x16x32_f16 v[96:99], v[148:151], v[196:199], v[96:99]
	s_setprio 0
	s_setprio 1
	v_mfma_f32_16x16x32_f16 v[64:67], v[152:155], v[168:171], v[64:67]
	v_mfma_f32_16x16x32_f16 v[56:59], v[160:163], v[168:171], v[56:59]
	v_mfma_f32_16x16x32_f16 v[52:55], v[152:155], v[176:179], v[52:55]
	v_mfma_f32_16x16x32_f16 v[48:51], v[160:163], v[176:179], v[48:51]
	v_mfma_f32_16x16x32_f16 v[44:47], v[152:155], v[184:187], v[44:47]
	v_mfma_f32_16x16x32_f16 v[40:43], v[160:163], v[184:187], v[40:43]
	v_mfma_f32_16x16x32_f16 v[36:39], v[152:155], v[192:195], v[36:39]
	v_mfma_f32_16x16x32_f16 v[32:35], v[160:163], v[192:195], v[32:35]
	v_mfma_f32_16x16x32_f16 v[64:67], v[156:159], v[172:175], v[64:67]
	v_mfma_f32_16x16x32_f16 v[56:59], v[164:167], v[172:175], v[56:59]
	v_mfma_f32_16x16x32_f16 v[52:55], v[156:159], v[180:183], v[52:55]
	v_mfma_f32_16x16x32_f16 v[48:51], v[164:167], v[180:183], v[48:51]
	v_mfma_f32_16x16x32_f16 v[44:47], v[156:159], v[188:191], v[44:47]
	v_mfma_f32_16x16x32_f16 v[40:43], v[164:167], v[188:191], v[40:43]
	v_mfma_f32_16x16x32_f16 v[36:39], v[156:159], v[196:199], v[36:39]
	v_mfma_f32_16x16x32_f16 v[32:35], v[164:167], v[196:199], v[32:35]
	s_setprio 0
	s_barrier
	ds_read_b128 v[168:171], v147 offset:16384
	ds_read_b128 v[172:175], v147 offset:17408
	ds_read_b128 v[176:179], v147 offset:18432
	ds_read_b128 v[180:183], v147 offset:19456
	ds_read_b128 v[184:187], v147 offset:20480
	ds_read_b128 v[188:191], v147 offset:21504
	ds_read_b128 v[192:195], v147 offset:22528
	ds_read_b128 v[196:199], v147 offset:23552
	s_mov_b32 s4, m0
	s_mov_b32 m0, s51
	s_nop 0
	global_load_lds_dwordx4 v143, s[46:47]
	s_mov_b32 m0, s4
	s_nop 0
	s_mov_b32 s4, m0
	s_mov_b32 m0, s56
	s_nop 0
	global_load_lds_dwordx4 v145, s[46:47]
	s_mov_b32 m0, s4
	s_add_u32 s4, s46, 0x80000
	s_addc_u32 s5, s47, 0
	s_mov_b32 s6, m0
	s_mov_b32 m0, s57
	s_nop 0
	global_load_lds_dwordx4 v143, s[4:5]
	s_mov_b32 m0, s6
	s_nop 0
	s_mov_b32 s6, m0
	s_mov_b32 m0, s60
	s_nop 0
	global_load_lds_dwordx4 v145, s[4:5]
	s_mov_b32 m0, s6
	s_mov_b32 s4, m0
	s_mov_b32 m0, s50
	s_nop 0
	global_load_lds_dwordx4 v142, s[48:49]
	s_mov_b32 m0, s4
	s_nop 0
	s_mov_b32 s4, m0
	s_mov_b32 m0, s61
	s_nop 0
	global_load_lds_dwordx4 v144, s[48:49]
	s_mov_b32 m0, s4
	s_waitcnt vmcnt(8)
	s_waitcnt lgkmcnt(0)
	s_barrier
; #define PG8_STAGE(bufoff, gbase, voff) do { _Pragma("unroll") for (int _i = 0; _i < 2; ++_i) glds16_s((gbase), (voff)[_i], ldsb + (unsigned)((bufoff) + _i * 8192)); } while (0)
; #define PG8_LDA(dst, b, h) do { _Pragma("unroll") for (int m = 0; m < 4; ++m) _Pragma("unroll") for (int k = 0; k < 2; ++k) dst[m][k] = *(const LAS h16x8*)(lds + PG8_SA(b, h) + aoff + m * 2048 + k * 1024); } while (0)
; #define PG8_LDB(dst, b, h) do { _Pragma("unroll") for (int n = 0; n < 2; ++n) _Pragma("unroll") for (int k = 0; k < 2; ++k) dst[n][k] = *(const LAS h16x8*)(lds + PG8_SB(b, h) + boff + n * 2048 + k * 1024); } while (0)
; #define PG8_MMA(ai, bj, At, Bt) do { __builtin_amdgcn_s_setprio(1); _Pragma("unroll") for (int m = 0; m < 4; ++m) _Pragma("unroll") for (int n = 0; n < 2; ++n) _Pragma("unroll") for (int k = 0; k < 2; ++k) \
;         acc[ai][bj][m][n] = mma_step<I8>(Bt[n][k], At[m][k], acc[ai][bj][m][n]); __builtin_amdgcn_s_setprio(0); } while (0)
; #define PG8_WAIT_V(n) asm volatile("s_waitcnt vmcnt(" #n ")" ::: "memory")
; #define PG8_WAIT_L(n) asm volatile("s_waitcnt lgkmcnt(" #n ")" ::: "memory")
; #define PG8_BAR __builtin_amdgcn_s_barrier()
; #define PG8_SCHED __builtin_amdgcn_sched_barrier(0)
; template <class Prob, class Epi, bool I8 = false, bool ALIGN_EPI = true, bool SP2 = true>
; __device__ __forceinline__ void gemm_phase(LAS unsigned char* lds, int wave, const Prob& P, const Epi& E) {
;     ...
;             PG8_WAIT_V(8); PG8_WAIT_L(0); PG8_BAR; PG8_MMA(1, 0, At, B0); PG8_MMA(1, 1, At, B1); PG8_BAR; PG8_SCHED;
;             PG8_LDB(B0, 1, 0); PG8_LDB(B1, 1, 1); PG8_SCHED; PG8_LDA(At, 1, 0); PG8_STAGE(PG8_SA(0, 1), a2 + hstepA, voffA);
;             PG8_WAIT_V(8); PG8_WAIT_L(0); PG8_BAR; PG8_MMA(0, 0, At, B0); PG8_MMA(0, 1, At, B1); PG8_BAR; PG8_SCHED;
	s_setprio 1
	s_waitcnt lgkmcnt(7)
	v_mfma_f32_16x16x32_f16 v[92:95], v[128:131], v[168:171], v[92:95]
	v_mfma_f32_16x16x32_f16 v[88:91], v[136:139], v[168:171], v[88:91]
	s_waitcnt lgkmcnt(5)
	v_mfma_f32_16x16x32_f16 v[84:87], v[128:131], v[176:179], v[84:87]
	v_mfma_f32_16x16x32_f16 v[80:83], v[136:139], v[176:179], v[80:83]
	s_waitcnt lgkmcnt(3)
	v_mfma_f32_16x16x32_f16 v[76:79], v[128:131], v[184:187], v[76:79]
	v_mfma_f32_16x16x32_f16 v[72:75], v[136:139], v[184:187], v[72:75]
	s_waitcnt lgkmcnt(1)
	v_mfma_f32_16x16x32_f16 v[68:71], v[128:131], v[192:195], v[68:71]
	v_mfma_f32_16x16x32_f16 v[60:63], v[136:139], v[192:195], v[60:63]
	v_mfma_f32_16x16x32_f16 v[92:95], v[132:135], v[172:175], v[92:95]
	v_mfma_f32_16x16x32_f16 v[88:91], v[148:151], v[172:175], v[88:91]
	v_mfma_f32_16x16x32_f16 v[84:87], v[132:135], v[180:183], v[84:87]
	v_mfma_f32_16x16x32_f16 v[80:83], v[148:151], v[180:183], v[80:83]
	v_mfma_f32_16x16x32_f16 v[76:79], v[132:135], v[188:191], v[76:79]
	v_mfma_f32_16x16x32_f16 v[72:75], v[148:151], v[188:191], v[72:75]
	s_waitcnt lgkmcnt(0)
	v_mfma_f32_16x16x32_f16 v[68:71], v[132:135], v[196:199], v[68:71]
	v_mfma_f32_16x16x32_f16 v[60:63], v[148:151], v[196:199], v[60:63]
	s_setprio 0
	s_setprio 1
	v_mfma_f32_16x16x32_f16 v[28:31], v[152:155], v[168:171], v[28:31]
	v_mfma_f32_16x16x32_f16 v[24:27], v[160:163], v[168:171], v[24:27]
	v_mfma_f32_16x16x32_f16 v[20:23], v[152:155], v[176:179], v[20:23]
	v_mfma_f32_16x16x32_f16 v[16:19], v[160:163], v[176:179], v[16:19]
	v_mfma_f32_16x16x32_f16 v[12:15], v[152:155], v[184:187], v[12:15]
	v_mfma_f32_16x16x32_f16 v[8:11], v[160:163], v[184:187], v[8:11]
	v_mfma_f32_16x16x32_f16 v[4:7], v[152:155], v[192:195], v[4:7]
	v_mfma_f32_16x16x32_f16 v[0:3], v[160:163], v[192:195], v[0:3]
	v_mfma_f32_16x16x32_f16 v[28:31], v[156:159], v[172:175], v[28:31]
	v_mfma_f32_16x16x32_f16 v[24:27], v[164:167], v[172:175], v[24:27]
	v_mfma_f32_16x16x32_f16 v[20:23], v[156:159], v[180:183], v[20:23]
	v_mfma_f32_16x16x32_f16 v[16:19], v[164:167], v[180:183], v[16:19]
	v_mfma_f32_16x16x32_f16 v[12:15], v[156:159], v[188:191], v[12:15]
	v_mfma_f32_16x16x32_f16 v[8:11], v[164:167], v[188:191], v[8:11]
	v_mfma_f32_16x16x32_f16 v[4:7], v[156:159], v[196:199], v[4:7]
	v_mfma_f32_16x16x32_f16 v[0:3], v[164:167], v[196:199], v[0:3]
	s_setprio 0
	s_barrier
	v_add_u32_e32 v140, 0x18000, v146
	ds_read_b128 v[128:131], v140
	ds_read_b128 v[132:135], v140 offset:1024
	ds_read_b128 v[136:139], v140 offset:2048
	ds_read_b128 v[148:151], v140 offset:3072
	v_add_u32_e32 v140, 0x1c000, v146
	ds_read_b128 v[152:155], v140
	ds_read_b128 v[156:159], v140 offset:1024
	ds_read_b128 v[160:163], v140 offset:2048
	ds_read_b128 v[164:167], v140 offset:3072
	ds_read_b128 v[168:171], v147 offset:32768
	ds_read_b128 v[172:175], v147 offset:33792
	ds_read_b128 v[176:179], v147 offset:34816
	ds_read_b128 v[180:183], v147 offset:35840
	ds_read_b128 v[184:187], v147 offset:36864
	ds_read_b128 v[188:191], v147 offset:37888
	ds_read_b128 v[192:195], v147 offset:38912
	ds_read_b128 v[196:199], v147 offset:39936
	s_add_u32 s4, s48, 0x80000
	s_addc_u32 s5, s49, 0
	s_mov_b32 s6, m0
	s_mov_b32 m0, s62
	s_nop 0
	global_load_lds_dwordx4 v142, s[4:5]
	s_mov_b32 m0, s6
	s_nop 0
	s_mov_b32 s6, m0
	s_mov_b32 m0, s63
	s_nop 0
	global_load_lds_dwordx4 v144, s[4:5]
	s_mov_b32 m0, s6
	s_waitcnt vmcnt(8)
	s_waitcnt lgkmcnt(0)
	s_barrier
	s_setprio 1
	s_waitcnt lgkmcnt(7)
	v_mfma_f32_16x16x32_f16 v[124:127], v[128:131], v[168:171], v[124:127]
	v_mfma_f32_16x16x32_f16 v[120:123], v[136:139], v[168:171], v[120:123]
	s_waitcnt lgkmcnt(5)
	v_mfma_f32_16x16x32_f16 v[116:119], v[128:131], v[176:179], v[116:119]
	v_mfma_f32_16x16x32_f16 v[112:115], v[136:139], v[176:179], v[112:115]
	s_waitcnt lgkmcnt(3)
	v_mfma_f32_16x16x32_f16 v[108:111], v[128:131], v[184:187], v[108:111]
	v_mfma_f32_16x16x32_f16 v[104:107], v[136:139], v[184:187], v[104:107]
	s_waitcnt lgkmcnt(1)
	v_mfma_f32_16x16x32_f16 v[100:103], v[128:131], v[192:195], v[100:103]
	v_mfma_f32_16x16x32_f16 v[96:99], v[136:139], v[192:195], v[96:99]
	v_mfma_f32_16x16x32_f16 v[124:127], v[132:135], v[172:175], v[124:127]
	v_mfma_f32_16x16x32_f16 v[120:123], v[148:151], v[172:175], v[120:123]
	v_mfma_f32_16x16x32_f16 v[116:119], v[132:135], v[180:183], v[116:119]
	v_mfma_f32_16x16x32_f16 v[112:115], v[148:151], v[180:183], v[112:115]
	v_mfma_f32_16x16x32_f16 v[108:111], v[132:135], v[188:191], v[108:111]
	v_mfma_f32_16x16x32_f16 v[104:107], v[148:151], v[188:191], v[104:107]
	s_waitcnt lgkmcnt(0)
	v_mfma_f32_16x16x32_f16 v[100:103], v[132:135], v[196:199], v[100:103]
	v_mfma_f32_16x16x32_f16 v[96:99], v[148:151], v[196:199], v[96:99]
	s_setprio 0
	s_setprio 1
	v_mfma_f32_16x16x32_f16 v[64:67], v[152:155], v[168:171], v[64:67]
	v_mfma_f32_16x16x32_f16 v[56:59], v[160:163], v[168:171], v[56:59]
	v_mfma_f32_16x16x32_f16 v[52:55], v[152:155], v[176:179], v[52:55]
	v_mfma_f32_16x16x32_f16 v[48:51], v[160:163], v[176:179], v[48:51]
	v_mfma_f32_16x16x32_f16 v[44:47], v[152:155], v[184:187], v[44:47]
	v_mfma_f32_16x16x32_f16 v[40:43], v[160:163], v[184:187], v[40:43]
	v_mfma_f32_16x16x32_f16 v[36:39], v[152:155], v[192:195], v[36:39]
	v_mfma_f32_16x16x32_f16 v[32:35], v[160:163], v[192:195], v[32:35]
	v_mfma_f32_16x16x32_f16 v[64:67], v[156:159], v[172:175], v[64:67]
	v_mfma_f32_16x16x32_f16 v[56:59], v[164:167], v[172:175], v[56:59]
	v_mfma_f32_16x16x32_f16 v[52:55], v[156:159], v[180:183], v[52:55]
	v_mfma_f32_16x16x32_f16 v[48:51], v[164:167], v[180:183], v[48:51]
	v_mfma_f32_16x16x32_f16 v[44:47], v[156:159], v[188:191], v[44:47]
	v_mfma_f32_16x16x32_f16 v[40:43], v[164:167], v[188:191], v[40:43]
	v_mfma_f32_16x16x32_f16 v[36:39], v[156:159], v[196:199], v[36:39]
	v_mfma_f32_16x16x32_f16 v[32:35], v[164:167], v[196:199], v[32:35]
	s_setprio 0
	s_barrier
; template <class Prob, class Epi, bool I8 = false, bool ALIGN_EPI = true, bool SP2 = true>
; __device__ __forceinline__ void gemm_phase(LAS unsigned char* lds, int wave, const Prob& P, const Epi& E) {
;     ...
;             PG8_LDA(At, 1, 1); PG8_STAGE(PG8_SB(1, 0), b3, voffB); PG8_STAGE(PG8_SB(1, 1), b3 + hstepB, voffB); PG8_STAGE(PG8_SA(1, 0), a3, voffA);
;             PG8_WAIT_V(8); PG8_WAIT_L(0); PG8_BAR; PG8_MMA(1, 0, At, B0); PG8_MMA(1, 1, At, B1); PG8_BAR; PG8_SCHED;
;             } else {
;             PG8_LDB(B0, 0, 0); PG8_SCHED; PG8_LDA(At, 0, 0); PG8_STAGE(PG8_SA(1, 1), a1 + hstepA, voffA);
;             PG8_WAIT_L(8); PG8_BAR; PG8_WAIT_L(0); PG8_MMA(0, 0, At, B0); PG8_BAR; PG8_SCHED;
;             PG8_LDB(B1, 0, 1); PG8_STAGE(PG8_SB(0, 0), b2, voffB);
;             PG8_BAR; PG8_WAIT_L(0); PG8_MMA(0, 1, At, B1); PG8_BAR;
;             PG8_LDA(At, 0, 1); PG8_STAGE(PG8_SA(0, 0), a2, voffA);
;             PG8_BAR; PG8_WAIT_L(0); PG8_MMA(1, 0, At, B0); PG8_BAR; PG8_SCHED;
;             PG8_STAGE(PG8_SB(0, 1), b2 + hstepB, voffB);
;             PG8_WAIT_V(6); PG8_BAR; PG8_MMA(1, 1, At, B1); PG8_BAR;
;             PG8_LDB(B0, 1, 0); PG8_SCHED; PG8_LDA(At, 1, 0); PG8_STAGE(PG8_SA(0, 1), a2 + hstepA, voffA);
;             PG8_WAIT_L(8); PG8_BAR; PG8_WAIT_L(0); PG8_MMA(0, 0, At, B0); PG8_BAR; PG8_SCHED;
;             PG8_LDB(B1, 1, 1); PG8_STAGE(PG8_SB(1, 0), b3, voffB);
;             PG8_BAR; PG8_WAIT_L(0); PG8_MMA(0, 1, At, B1); PG8_BAR;
;             PG8_LDA(At, 1, 1); PG8_STAGE(PG8_SA(1, 0), a3, voffA);
;             PG8_BAR; PG8_WAIT_L(0); PG8_MMA(1, 0, At, B0); PG8_BAR; PG8_SCHED;
;             PG8_STAGE(PG8_SB(1, 1), b3 + hstepB, voffB);
;             PG8_WAIT_V(6); PG8_BAR; PG8_MMA(1, 1, At, B1); PG8_BAR;
;             }
;         }
;         if constexpr (ALIGN_EPI) { if (wr == 0) PG8_BAR; }
;     __device__ __forceinline__ void operator()(Acc& acc, const Unit& u, int wr, int wc, int fr, int fq, LAS unsigned char* lds, int tid) const {
;     ...
;             for (int ai = 0; ai < 2; ++ai) {
;                 h16x8 xv[4];
;                 f32x2 st[4]; float rs[4];
; #pragma unroll
;                 for (int m = 0; m < 4; ++m) { const unsigned row = u.pm * 256 + ai * 128 + wr * 64 + m * 16 + fr; xv[m] = *(const h16x8*)(X + (size_t)row * D + colt);
;                     if constexpr (LNX) st[m] = *(const f32x2*)((const char*)stats + (row << 3));
	ds_read_b128 v[168:171], v147 offset:49152
	ds_read_b128 v[172:175], v147 offset:50176
	ds_read_b128 v[176:179], v147 offset:51200
	ds_read_b128 v[180:183], v147 offset:52224
	ds_read_b128 v[184:187], v147 offset:53248
	ds_read_b128 v[188:191], v147 offset:54272
	ds_read_b128 v[192:195], v147 offset:55296
	ds_read_b128 v[196:199], v147 offset:56320
	s_add_u32 s4, s46, 0x80
	s_addc_u32 s5, s47, 0
	s_mov_b32 s6, m0
	s_mov_b32 m0, s69
	s_nop 0
	global_load_lds_dwordx4 v143, s[4:5]
	s_mov_b32 m0, s6
	s_nop 0
	s_mov_b32 s6, m0
	s_mov_b32 m0, s72
	s_nop 0
	global_load_lds_dwordx4 v145, s[4:5]
	s_mov_b32 m0, s6
	s_add_u32 s4, s46, 0x80080
	s_addc_u32 s5, s47, 0
	s_mov_b32 s6, m0
	s_mov_b32 m0, s75
	s_nop 0
	global_load_lds_dwordx4 v143, s[4:5]
	s_mov_b32 m0, s6
	s_nop 0
	s_mov_b32 s6, m0
	s_mov_b32 m0, s76
	s_nop 0
	global_load_lds_dwordx4 v145, s[4:5]
	s_mov_b32 m0, s6
	s_mov_b32 s4, m0
	s_mov_b32 m0, s73
	s_nop 0
	global_load_lds_dwordx4 v142, s[44:45]
	s_mov_b32 m0, s4
	s_nop 0
	s_mov_b32 s4, m0
	s_mov_b32 m0, s74
	s_nop 0
	global_load_lds_dwordx4 v144, s[44:45]
	s_mov_b32 m0, s4
	s_waitcnt vmcnt(8)
	s_waitcnt lgkmcnt(0)
	s_barrier
	s_setprio 1
	s_waitcnt lgkmcnt(7)
	v_mfma_f32_16x16x32_f16 v[92:95], v[128:131], v[168:171], v[92:95]
	v_mfma_f32_16x16x32_f16 v[88:91], v[136:139], v[168:171], v[88:91]
	s_waitcnt lgkmcnt(5)
	v_mfma_f32_16x16x32_f16 v[84:87], v[128:131], v[176:179], v[84:87]
	v_mfma_f32_16x16x32_f16 v[80:83], v[136:139], v[176:179], v[80:83]
	s_waitcnt lgkmcnt(3)
	v_mfma_f32_16x16x32_f16 v[76:79], v[128:131], v[184:187], v[76:79]
	v_mfma_f32_16x16x32_f16 v[72:75], v[136:139], v[184:187], v[72:75]
	s_waitcnt lgkmcnt(1)
	v_mfma_f32_16x16x32_f16 v[68:71], v[128:131], v[192:195], v[68:71]
	v_mfma_f32_16x16x32_f16 v[60:63], v[136:139], v[192:195], v[60:63]
	v_mfma_f32_16x16x32_f16 v[92:95], v[132:135], v[172:175], v[92:95]
	v_mfma_f32_16x16x32_f16 v[88:91], v[148:151], v[172:175], v[88:91]
	v_mfma_f32_16x16x32_f16 v[84:87], v[132:135], v[180:183], v[84:87]
	v_mfma_f32_16x16x32_f16 v[80:83], v[148:151], v[180:183], v[80:83]
	v_mfma_f32_16x16x32_f16 v[76:79], v[132:135], v[188:191], v[76:79]
	v_mfma_f32_16x16x32_f16 v[72:75], v[148:151], v[188:191], v[72:75]
	s_waitcnt lgkmcnt(0)
	v_mfma_f32_16x16x32_f16 v[68:71], v[132:135], v[196:199], v[68:71]
	v_mfma_f32_16x16x32_f16 v[60:63], v[148:151], v[196:199], v[60:63]
	s_setprio 0
	s_setprio 1
	v_mfma_f32_16x16x32_f16 v[28:31], v[152:155], v[168:171], v[28:31]
	v_mfma_f32_16x16x32_f16 v[24:27], v[160:163], v[168:171], v[24:27]
	v_mfma_f32_16x16x32_f16 v[20:23], v[152:155], v[176:179], v[20:23]
	v_mfma_f32_16x16x32_f16 v[16:19], v[160:163], v[176:179], v[16:19]
	v_mfma_f32_16x16x32_f16 v[12:15], v[152:155], v[184:187], v[12:15]
	v_mfma_f32_16x16x32_f16 v[8:11], v[160:163], v[184:187], v[8:11]
	v_mfma_f32_16x16x32_f16 v[4:7], v[152:155], v[192:195], v[4:7]
	v_mfma_f32_16x16x32_f16 v[0:3], v[160:163], v[192:195], v[0:3]
	v_mfma_f32_16x16x32_f16 v[28:31], v[156:159], v[172:175], v[28:31]
	v_mfma_f32_16x16x32_f16 v[24:27], v[164:167], v[172:175], v[24:27]
	v_mfma_f32_16x16x32_f16 v[20:23], v[156:159], v[180:183], v[20:23]
	v_mfma_f32_16x16x32_f16 v[16:19], v[164:167], v[180:183], v[16:19]
	v_mfma_f32_16x16x32_f16 v[12:15], v[156:159], v[188:191], v[12:15]
	v_mfma_f32_16x16x32_f16 v[8:11], v[164:167], v[188:191], v[8:11]
	v_mfma_f32_16x16x32_f16 v[4:7], v[156:159], v[196:199], v[4:7]
	v_mfma_f32_16x16x32_f16 v[0:3], v[164:167], v[196:199], v[0:3]
	s_setprio 0
	s_barrier
	s_add_i32 s1, s1, 2
	s_add_u32 s85, s85, 0x100
	s_addc_u32 s86, s86, 0
	s_add_u32 s87, s87, 0x100
	s_addc_u32 s0, s0, 0
	s_add_u32 s40, s40, 0x100
	s_addc_u32 s41, s41, 0
	s_cmp_gt_u32 s1, 29
	s_cbranch_scc0 .LBB0_464
	v_mbcnt_lo_u32_b32 v128, -1, 0
	v_mbcnt_hi_u32_b32 v128, -1, v128
	s_lshl_b32 s0, s82, 8
	s_lshl_b32 s1, s81, 8
	v_lshrrev_b32_e32 v129, 1, v128
	s_add_i32 s1, s1, s64
	v_and_or_b32 v129, v129, 24, s0
	v_and_or_b32 v130, v128, 15, s1
	v_or_b32_e32 v129, s68, v129
	v_lshlrev_b32_e32 v130, 12, v130
	v_lshl_add_u32 v128, v129, 1, v130
	v_add_u32_e32 v129, 0x10000, v128
	v_add_u32_e32 v130, 0x20000, v128
	v_add_u32_e32 v131, 0x30000, v128
	v_add_u32_e32 v132, 0x80000, v128
	v_add_u32_e32 v133, 0x90000, v128
	v_add_u32_e32 v134, 0xa0000, v128
	v_add_u32_e32 v135, 0xb0000, v128
	global_load_dwordx4 v[148:151], v128, s[54:55]
	global_load_dwordx4 v[152:155], v129, s[54:55]
	global_load_dwordx4 v[156:159], v130, s[54:55]
	global_load_dwordx4 v[160:163], v131, s[54:55]
	global_load_dwordx4 v[164:167], v132, s[54:55]
	global_load_dwordx4 v[168:171], v133, s[54:55]
	global_load_dwordx4 v[172:175], v134, s[54:55]
	global_load_dwordx4 v[176:179], v135, s[54:55]
	global_load_dwordx4 v[180:183], v128, s[54:55] offset:256
	global_load_dwordx4 v[184:187], v129, s[54:55] offset:256
	global_load_dwordx4 v[188:191], v130, s[54:55] offset:256
	global_load_dwordx4 v[192:195], v131, s[54:55] offset:256
	global_load_dwordx4 v[196:199], v132, s[54:55] offset:256
	global_load_dwordx4 v[200:203], v133, s[54:55] offset:256
	global_load_dwordx4 v[204:207], v134, s[54:55] offset:256
	global_load_dwordx4 v[212:215], v135, s[54:55] offset:256
	s_and_b64 vcc, exec, s[16:17]
	s_cbranch_vccz .LBB0_467
	s_barrier
;     __device__ __forceinline__ void operator()(Acc& acc, const Unit& u, int wr, int wc, int fr, int fq, LAS unsigned char* lds, int tid) const {
;     ...
;             for (int ai = 0; ai < 2; ++ai) {
;                 h16x8 xv[4];
;                 f32x2 st[4]; float rs[4];
; #pragma unroll
;                 for (int m = 0; m < 4; ++m) { const unsigned row = u.pm * 256 + ai * 128 + wr * 64 + m * 16 + fr; xv[m] = *(const h16x8*)(X + (size_t)row * D + colt);
;                     if constexpr (LNX) st[m] = *(const f32x2*)((const char*)stats + (row << 3));
;                     if constexpr (I8) rs[m] = *(const float*)((const char*)sa + (row << 2)); }
;                 asm volatile("" ::: "memory");
; #pragma unroll
;                 for (int m = 0; m < 4; ++m) {
;                     const unsigned row = u.pm * 256 + ai * 128 + wr * 64 + m * 16 + fr;
;                     f32x4 z[2];
; #pragma unroll
;                     for (int n = 0; n < 2; ++n) {
;                         f32x4 a = acc[ai][bj][m][n];
;                         if constexpr (I8) { const pg8::i32x4 iv = __builtin_bit_cast(pg8::i32x4, a); a = __builtin_convertvector(iv, f32x4) * (cs[n] * rs[m]); }
; #pragma unroll
;                         for (int e = 0; e < 4; ++e) {
;                             if constexpr (LNX) { const float t = ((float)xv[m][4 * n + e] - st[m].x) * st[m].y; z[n][e] = t * ga[n][e] + (ba[n][e] + a[e]); }
;                             else z[n][e] = (float)xv[m][4 * n + e] * ALPHA + a[e]; }
;                     }
;                     store_h8(X + (size_t)row * D + colt, z[0], z[1]);
;                 }
;                 asm volatile("" ::: "memory");
.LBB0_467:
	s_mov_b64 s[40:41], -1
	s_andn2_b64 vcc, exec, s[36:37]
	s_waitcnt vmcnt(15)
	v_cvt_f32_f16_e32 v136, v148
	v_cvt_f32_f16_sdwa v137, v148 dst_sel:DWORD dst_unused:UNUSED_PAD src0_sel:WORD_1
	v_cvt_f32_f16_e32 v138, v149
	v_cvt_f32_f16_sdwa v139, v149 dst_sel:DWORD dst_unused:UNUSED_PAD src0_sel:WORD_1
	v_pk_fma_f32 v[124:125], v[136:137], s[34:35], v[124:125] op_sel_hi:[1,0,1]
	v_pk_fma_f32 v[126:127], v[138:139], s[34:35], v[126:127] op_sel_hi:[1,0,1]
	v_cvt_f32_f16_e32 v136, v150
	v_cvt_f32_f16_sdwa v137, v150 dst_sel:DWORD dst_unused:UNUSED_PAD src0_sel:WORD_1
	v_cvt_f32_f16_e32 v138, v151
	v_cvt_f32_f16_sdwa v139, v151 dst_sel:DWORD dst_unused:UNUSED_PAD src0_sel:WORD_1
	v_pk_fma_f32 v[120:121], v[136:137], s[34:35], v[120:121] op_sel_hi:[1,0,1]
	v_pk_fma_f32 v[122:123], v[138:139], s[34:35], v[122:123] op_sel_hi:[1,0,1]
	v_cvt_pk_f16_f32 v124, v124, v125
	v_cvt_pk_f16_f32 v125, v126, v127
	v_cvt_pk_f16_f32 v126, v120, v121
	v_cvt_pk_f16_f32 v127, v122, v123
	global_store_dwordx4 v128, v[124:127], s[54:55]
	s_waitcnt vmcnt(15)
	v_cvt_f32_f16_e32 v136, v152
	v_cvt_f32_f16_sdwa v137, v152 dst_sel:DWORD dst_unused:UNUSED_PAD src0_sel:WORD_1
	v_cvt_f32_f16_e32 v138, v153
	v_cvt_f32_f16_sdwa v139, v153 dst_sel:DWORD dst_unused:UNUSED_PAD src0_sel:WORD_1
	v_pk_fma_f32 v[116:117], v[136:137], s[34:35], v[116:117] op_sel_hi:[1,0,1]
	v_pk_fma_f32 v[118:119], v[138:139], s[34:35], v[118:119] op_sel_hi:[1,0,1]
	v_cvt_f32_f16_e32 v136, v154
	v_cvt_f32_f16_sdwa v137, v154 dst_sel:DWORD dst_unused:UNUSED_PAD src0_sel:WORD_1
	v_cvt_f32_f16_e32 v138, v155
	v_cvt_f32_f16_sdwa v139, v155 dst_sel:DWORD dst_unused:UNUSED_PAD src0_sel:WORD_1
	v_pk_fma_f32 v[112:113], v[136:137], s[34:35], v[112:113] op_sel_hi:[1,0,1]
	v_pk_fma_f32 v[114:115], v[138:139], s[34:35], v[114:115] op_sel_hi:[1,0,1]
	v_cvt_pk_f16_f32 v116, v116, v117
	v_cvt_pk_f16_f32 v117, v118, v119
	v_cvt_pk_f16_f32 v118, v112, v113
	v_cvt_pk_f16_f32 v119, v114, v115
	global_store_dwordx4 v129, v[116:119], s[54:55]
	s_waitcnt vmcnt(15)
	v_cvt_f32_f16_e32 v136, v156
	v_cvt_f32_f16_sdwa v137, v156 dst_sel:DWORD dst_unused:UNUSED_PAD src0_sel:WORD_1
	v_cvt_f32_f16_e32 v138, v157
	v_cvt_f32_f16_sdwa v139, v157 dst_sel:DWORD dst_unused:UNUSED_PAD src0_sel:WORD_1
	v_pk_fma_f32 v[108:109], v[136:137], s[34:35], v[108:109] op_sel_hi:[1,0,1]
	v_pk_fma_f32 v[110:111], v[138:139], s[34:35], v[110:111] op_sel_hi:[1,0,1]
	v_cvt_f32_f16_e32 v136, v158
	v_cvt_f32_f16_sdwa v137, v158 dst_sel:DWORD dst_unused:UNUSED_PAD src0_sel:WORD_1
	v_cvt_f32_f16_e32 v138, v159
	v_cvt_f32_f16_sdwa v139, v159 dst_sel:DWORD dst_unused:UNUSED_PAD src0_sel:WORD_1
	v_pk_fma_f32 v[104:105], v[136:137], s[34:35], v[104:105] op_sel_hi:[1,0,1]
	v_pk_fma_f32 v[106:107], v[138:139], s[34:35], v[106:107] op_sel_hi:[1,0,1]
	v_cvt_pk_f16_f32 v108, v108, v109
	v_cvt_pk_f16_f32 v109, v110, v111
	v_cvt_pk_f16_f32 v110, v104, v105
	v_cvt_pk_f16_f32 v111, v106, v107
	global_store_dwordx4 v130, v[108:111], s[54:55]
	s_waitcnt vmcnt(15)
	v_cvt_f32_f16_e32 v136, v160
	v_cvt_f32_f16_sdwa v137, v160 dst_sel:DWORD dst_unused:UNUSED_PAD src0_sel:WORD_1
	v_cvt_f32_f16_e32 v138, v161
	v_cvt_f32_f16_sdwa v139, v161 dst_sel:DWORD dst_unused:UNUSED_PAD src0_sel:WORD_1
	v_pk_fma_f32 v[100:101], v[136:137], s[34:35], v[100:101] op_sel_hi:[1,0,1]
	v_pk_fma_f32 v[102:103], v[138:139], s[34:35], v[102:103] op_sel_hi:[1,0,1]
	v_cvt_f32_f16_e32 v136, v162
	v_cvt_f32_f16_sdwa v137, v162 dst_sel:DWORD dst_unused:UNUSED_PAD src0_sel:WORD_1
	v_cvt_f32_f16_e32 v138, v163
	v_cvt_f32_f16_sdwa v139, v163 dst_sel:DWORD dst_unused:UNUSED_PAD src0_sel:WORD_1
	v_pk_fma_f32 v[96:97], v[136:137], s[34:35], v[96:97] op_sel_hi:[1,0,1]
	v_pk_fma_f32 v[98:99], v[138:139], s[34:35], v[98:99] op_sel_hi:[1,0,1]
	v_cvt_pk_f16_f32 v100, v100, v101
	v_cvt_pk_f16_f32 v101, v102, v103
	v_cvt_pk_f16_f32 v102, v96, v97
	v_cvt_pk_f16_f32 v103, v98, v99
	global_store_dwordx4 v131, v[100:103], s[54:55]
	s_waitcnt vmcnt(15)
	v_cvt_f32_f16_e32 v136, v164
	v_cvt_f32_f16_sdwa v137, v164 dst_sel:DWORD dst_unused:UNUSED_PAD src0_sel:WORD_1
	v_cvt_f32_f16_e32 v138, v165
	v_cvt_f32_f16_sdwa v139, v165 dst_sel:DWORD dst_unused:UNUSED_PAD src0_sel:WORD_1
	v_pk_fma_f32 v[92:93], v[136:137], s[34:35], v[92:93] op_sel_hi:[1,0,1]
	v_pk_fma_f32 v[94:95], v[138:139], s[34:35], v[94:95] op_sel_hi:[1,0,1]
	v_cvt_f32_f16_e32 v136, v166
	v_cvt_f32_f16_sdwa v137, v166 dst_sel:DWORD dst_unused:UNUSED_PAD src0_sel:WORD_1
	v_cvt_f32_f16_e32 v138, v167
	v_cvt_f32_f16_sdwa v139, v167 dst_sel:DWORD dst_unused:UNUSED_PAD src0_sel:WORD_1
	v_pk_fma_f32 v[88:89], v[136:137], s[34:35], v[88:89] op_sel_hi:[1,0,1]
	v_pk_fma_f32 v[90:91], v[138:139], s[34:35], v[90:91] op_sel_hi:[1,0,1]
	v_cvt_pk_f16_f32 v92, v92, v93
	v_cvt_pk_f16_f32 v93, v94, v95
	v_cvt_pk_f16_f32 v94, v88, v89
	v_cvt_pk_f16_f32 v95, v90, v91
	global_store_dwordx4 v132, v[92:95], s[54:55]
	s_waitcnt vmcnt(15)
	v_cvt_f32_f16_e32 v136, v168
	v_cvt_f32_f16_sdwa v137, v168 dst_sel:DWORD dst_unused:UNUSED_PAD src0_sel:WORD_1
	v_cvt_f32_f16_e32 v138, v169
	v_cvt_f32_f16_sdwa v139, v169 dst_sel:DWORD dst_unused:UNUSED_PAD src0_sel:WORD_1
	v_pk_fma_f32 v[84:85], v[136:137], s[34:35], v[84:85] op_sel_hi:[1,0,1]
	v_pk_fma_f32 v[86:87], v[138:139], s[34:35], v[86:87] op_sel_hi:[1,0,1]
	v_cvt_f32_f16_e32 v136, v170
	v_cvt_f32_f16_sdwa v137, v170 dst_sel:DWORD dst_unused:UNUSED_PAD src0_sel:WORD_1
	v_cvt_f32_f16_e32 v138, v171
	v_cvt_f32_f16_sdwa v139, v171 dst_sel:DWORD dst_unused:UNUSED_PAD src0_sel:WORD_1
	v_pk_fma_f32 v[80:81], v[136:137], s[34:35], v[80:81] op_sel_hi:[1,0,1]
	v_pk_fma_f32 v[82:83], v[138:139], s[34:35], v[82:83] op_sel_hi:[1,0,1]
	v_cvt_pk_f16_f32 v84, v84, v85
	v_cvt_pk_f16_f32 v85, v86, v87
	v_cvt_pk_f16_f32 v86, v80, v81
	v_cvt_pk_f16_f32 v87, v82, v83
	global_store_dwordx4 v133, v[84:87], s[54:55]
	s_waitcnt vmcnt(15)
;     __device__ __forceinline__ void operator()(Acc& acc, const Unit& u, int wr, int wc, int fr, int fq, LAS unsigned char* lds, int tid) const {
;     ...
; #pragma unroll
;                 for (int m = 0; m < 4; ++m) {
;                     const unsigned row = u.pm * 256 + ai * 128 + wr * 64 + m * 16 + fr;
;                     f32x4 z[2];
; #pragma unroll
;                     for (int n = 0; n < 2; ++n) {
;                         f32x4 a = acc[ai][bj][m][n];
;                         if constexpr (I8) { const pg8::i32x4 iv = __builtin_bit_cast(pg8::i32x4, a); a = __builtin_convertvector(iv, f32x4) * (cs[n] * rs[m]); }
; #pragma unroll
;                         for (int e = 0; e < 4; ++e) {
;                             if constexpr (LNX) { const float t = ((float)xv[m][4 * n + e] - st[m].x) * st[m].y; z[n][e] = t * ga[n][e] + (ba[n][e] + a[e]); }
;                             else z[n][e] = (float)xv[m][4 * n + e] * ALPHA + a[e]; }
;                     }
;                     store_h8(X + (size_t)row * D + colt, z[0], z[1]);
;                 }
;                 asm volatile("" ::: "memory");
	v_cvt_f32_f16_e32 v136, v172
	v_cvt_f32_f16_sdwa v137, v172 dst_sel:DWORD dst_unused:UNUSED_PAD src0_sel:WORD_1
	v_cvt_f32_f16_e32 v138, v173
	v_cvt_f32_f16_sdwa v139, v173 dst_sel:DWORD dst_unused:UNUSED_PAD src0_sel:WORD_1
	v_pk_fma_f32 v[76:77], v[136:137], s[34:35], v[76:77] op_sel_hi:[1,0,1]
	v_pk_fma_f32 v[78:79], v[138:139], s[34:35], v[78:79] op_sel_hi:[1,0,1]
	v_cvt_f32_f16_e32 v136, v174
	v_cvt_f32_f16_sdwa v137, v174 dst_sel:DWORD dst_unused:UNUSED_PAD src0_sel:WORD_1
	v_cvt_f32_f16_e32 v138, v175
	v_cvt_f32_f16_sdwa v139, v175 dst_sel:DWORD dst_unused:UNUSED_PAD src0_sel:WORD_1
	v_pk_fma_f32 v[72:73], v[136:137], s[34:35], v[72:73] op_sel_hi:[1,0,1]
	v_pk_fma_f32 v[74:75], v[138:139], s[34:35], v[74:75] op_sel_hi:[1,0,1]
	v_cvt_pk_f16_f32 v76, v76, v77
	v_cvt_pk_f16_f32 v77, v78, v79
	v_cvt_pk_f16_f32 v78, v72, v73
	v_cvt_pk_f16_f32 v79, v74, v75
	global_store_dwordx4 v134, v[76:79], s[54:55]
	s_waitcnt vmcnt(15)
	v_cvt_f32_f16_e32 v136, v176
	v_cvt_f32_f16_sdwa v137, v176 dst_sel:DWORD dst_unused:UNUSED_PAD src0_sel:WORD_1
	v_cvt_f32_f16_e32 v138, v177
	v_cvt_f32_f16_sdwa v139, v177 dst_sel:DWORD dst_unused:UNUSED_PAD src0_sel:WORD_1
	v_pk_fma_f32 v[68:69], v[136:137], s[34:35], v[68:69] op_sel_hi:[1,0,1]
	v_pk_fma_f32 v[70:71], v[138:139], s[34:35], v[70:71] op_sel_hi:[1,0,1]
	v_cvt_f32_f16_e32 v136, v178
	v_cvt_f32_f16_sdwa v137, v178 dst_sel:DWORD dst_unused:UNUSED_PAD src0_sel:WORD_1
	v_cvt_f32_f16_e32 v138, v179
	v_cvt_f32_f16_sdwa v139, v179 dst_sel:DWORD dst_unused:UNUSED_PAD src0_sel:WORD_1
	v_pk_fma_f32 v[60:61], v[136:137], s[34:35], v[60:61] op_sel_hi:[1,0,1]
	v_pk_fma_f32 v[62:63], v[138:139], s[34:35], v[62:63] op_sel_hi:[1,0,1]
	v_cvt_pk_f16_f32 v68, v68, v69
	v_cvt_pk_f16_f32 v69, v70, v71
	v_cvt_pk_f16_f32 v70, v60, v61
	v_cvt_pk_f16_f32 v71, v62, v63
	global_store_dwordx4 v135, v[68:71], s[54:55]
	s_waitcnt vmcnt(15)
	v_cvt_f32_f16_e32 v136, v180
	v_cvt_f32_f16_sdwa v137, v180 dst_sel:DWORD dst_unused:UNUSED_PAD src0_sel:WORD_1
	v_cvt_f32_f16_e32 v138, v181
	v_cvt_f32_f16_sdwa v139, v181 dst_sel:DWORD dst_unused:UNUSED_PAD src0_sel:WORD_1
	v_pk_fma_f32 v[64:65], v[136:137], s[34:35], v[64:65] op_sel_hi:[1,0,1]
	v_pk_fma_f32 v[66:67], v[138:139], s[34:35], v[66:67] op_sel_hi:[1,0,1]
	v_cvt_f32_f16_e32 v136, v182
	v_cvt_f32_f16_sdwa v137, v182 dst_sel:DWORD dst_unused:UNUSED_PAD src0_sel:WORD_1
	v_cvt_f32_f16_e32 v138, v183
	v_cvt_f32_f16_sdwa v139, v183 dst_sel:DWORD dst_unused:UNUSED_PAD src0_sel:WORD_1
	v_pk_fma_f32 v[56:57], v[136:137], s[34:35], v[56:57] op_sel_hi:[1,0,1]
	v_pk_fma_f32 v[58:59], v[138:139], s[34:35], v[58:59] op_sel_hi:[1,0,1]
	v_cvt_pk_f16_f32 v64, v64, v65
	v_cvt_pk_f16_f32 v65, v66, v67
	v_cvt_pk_f16_f32 v66, v56, v57
	v_cvt_pk_f16_f32 v67, v58, v59
	global_store_dwordx4 v128, v[64:67], s[54:55] offset:256
	s_waitcnt vmcnt(15)
	v_cvt_f32_f16_e32 v136, v184
	v_cvt_f32_f16_sdwa v137, v184 dst_sel:DWORD dst_unused:UNUSED_PAD src0_sel:WORD_1
	v_cvt_f32_f16_e32 v138, v185
	v_cvt_f32_f16_sdwa v139, v185 dst_sel:DWORD dst_unused:UNUSED_PAD src0_sel:WORD_1
	v_pk_fma_f32 v[52:53], v[136:137], s[34:35], v[52:53] op_sel_hi:[1,0,1]
	v_pk_fma_f32 v[54:55], v[138:139], s[34:35], v[54:55] op_sel_hi:[1,0,1]
	v_cvt_f32_f16_e32 v136, v186
	v_cvt_f32_f16_sdwa v137, v186 dst_sel:DWORD dst_unused:UNUSED_PAD src0_sel:WORD_1
	v_cvt_f32_f16_e32 v138, v187
	v_cvt_f32_f16_sdwa v139, v187 dst_sel:DWORD dst_unused:UNUSED_PAD src0_sel:WORD_1
	v_pk_fma_f32 v[48:49], v[136:137], s[34:35], v[48:49] op_sel_hi:[1,0,1]
	v_pk_fma_f32 v[50:51], v[138:139], s[34:35], v[50:51] op_sel_hi:[1,0,1]
	v_cvt_pk_f16_f32 v52, v52, v53
	v_cvt_pk_f16_f32 v53, v54, v55
	v_cvt_pk_f16_f32 v54, v48, v49
	v_cvt_pk_f16_f32 v55, v50, v51
	global_store_dwordx4 v129, v[52:55], s[54:55] offset:256
	s_waitcnt vmcnt(15)
	v_cvt_f32_f16_e32 v136, v188
	v_cvt_f32_f16_sdwa v137, v188 dst_sel:DWORD dst_unused:UNUSED_PAD src0_sel:WORD_1
	v_cvt_f32_f16_e32 v138, v189
	v_cvt_f32_f16_sdwa v139, v189 dst_sel:DWORD dst_unused:UNUSED_PAD src0_sel:WORD_1
	v_pk_fma_f32 v[44:45], v[136:137], s[34:35], v[44:45] op_sel_hi:[1,0,1]
	v_pk_fma_f32 v[46:47], v[138:139], s[34:35], v[46:47] op_sel_hi:[1,0,1]
	v_cvt_f32_f16_e32 v136, v190
	v_cvt_f32_f16_sdwa v137, v190 dst_sel:DWORD dst_unused:UNUSED_PAD src0_sel:WORD_1
	v_cvt_f32_f16_e32 v138, v191
	v_cvt_f32_f16_sdwa v139, v191 dst_sel:DWORD dst_unused:UNUSED_PAD src0_sel:WORD_1
	v_pk_fma_f32 v[40:41], v[136:137], s[34:35], v[40:41] op_sel_hi:[1,0,1]
	v_pk_fma_f32 v[42:43], v[138:139], s[34:35], v[42:43] op_sel_hi:[1,0,1]
	v_cvt_pk_f16_f32 v44, v44, v45
	v_cvt_pk_f16_f32 v45, v46, v47
	v_cvt_pk_f16_f32 v46, v40, v41
	v_cvt_pk_f16_f32 v47, v42, v43
	global_store_dwordx4 v130, v[44:47], s[54:55] offset:256
	s_waitcnt vmcnt(15)
; #define PG8_BAR __builtin_amdgcn_s_barrier()
; template <class Prob, class Epi, bool I8 = false, bool ALIGN_EPI = true, bool SP2 = true>
; __device__ __forceinline__ void gemm_phase(LAS unsigned char* lds, int wave, const Prob& P, const Epi& E) {
;     ...
;         if (!has_next) break;
;         if (!cur.keep) {
; #pragma unroll
;         for (int a = 0; a < 2; ++a)
; #pragma unroll
;             for (int b = 0; b < 2; ++b)
; #pragma unroll
;                 for (int m = 0; m < 4; ++m)
; #pragma unroll
;                     for (int n = 0; n < 2; ++n) acc[a][b][m][n] = (f32x4){0.f, 0.f, 0.f, 0.f};
;         }
;         cur = nxt; cA = nA; cB = nB; ++ui;
;         if constexpr (ALIGN_EPI) { if (wr == 1) PG8_BAR; }
;     __device__ __forceinline__ void operator()(Acc& acc, const Unit& u, int wr, int wc, int fr, int fq, LAS unsigned char* lds, int tid) const {
;     ...
; #pragma unroll
;                 for (int m = 0; m < 4; ++m) {
;                     const unsigned row = u.pm * 256 + ai * 128 + wr * 64 + m * 16 + fr;
;                     f32x4 z[2];
; #pragma unroll
;                     for (int n = 0; n < 2; ++n) {
;                         f32x4 a = acc[ai][bj][m][n];
;                         if constexpr (I8) { const pg8::i32x4 iv = __builtin_bit_cast(pg8::i32x4, a); a = __builtin_convertvector(iv, f32x4) * (cs[n] * rs[m]); }
; #pragma unroll
;                         for (int e = 0; e < 4; ++e) {
;                             if constexpr (LNX) { const float t = ((float)xv[m][4 * n + e] - st[m].x) * st[m].y; z[n][e] = t * ga[n][e] + (ba[n][e] + a[e]); }
;                             else z[n][e] = (float)xv[m][4 * n + e] * ALPHA + a[e]; }
;                     }
;                     store_h8(X + (size_t)row * D + colt, z[0], z[1]);
;                 }
;                 asm volatile("" ::: "memory");
	v_cvt_f32_f16_e32 v136, v192
	v_cvt_f32_f16_sdwa v137, v192 dst_sel:DWORD dst_unused:UNUSED_PAD src0_sel:WORD_1
	v_cvt_f32_f16_e32 v138, v193
	v_cvt_f32_f16_sdwa v139, v193 dst_sel:DWORD dst_unused:UNUSED_PAD src0_sel:WORD_1
	v_pk_fma_f32 v[36:37], v[136:137], s[34:35], v[36:37] op_sel_hi:[1,0,1]
	v_pk_fma_f32 v[38:39], v[138:139], s[34:35], v[38:39] op_sel_hi:[1,0,1]
	v_cvt_f32_f16_e32 v136, v194
	v_cvt_f32_f16_sdwa v137, v194 dst_sel:DWORD dst_unused:UNUSED_PAD src0_sel:WORD_1
	v_cvt_f32_f16_e32 v138, v195
	v_cvt_f32_f16_sdwa v139, v195 dst_sel:DWORD dst_unused:UNUSED_PAD src0_sel:WORD_1
	v_pk_fma_f32 v[32:33], v[136:137], s[34:35], v[32:33] op_sel_hi:[1,0,1]
	v_pk_fma_f32 v[34:35], v[138:139], s[34:35], v[34:35] op_sel_hi:[1,0,1]
	v_cvt_pk_f16_f32 v36, v36, v37
	v_cvt_pk_f16_f32 v37, v38, v39
	v_cvt_pk_f16_f32 v38, v32, v33
	v_cvt_pk_f16_f32 v39, v34, v35
	global_store_dwordx4 v131, v[36:39], s[54:55] offset:256
	s_waitcnt vmcnt(15)
	v_cvt_f32_f16_e32 v136, v196
	v_cvt_f32_f16_sdwa v137, v196 dst_sel:DWORD dst_unused:UNUSED_PAD src0_sel:WORD_1
	v_cvt_f32_f16_e32 v138, v197
	v_cvt_f32_f16_sdwa v139, v197 dst_sel:DWORD dst_unused:UNUSED_PAD src0_sel:WORD_1
	v_pk_fma_f32 v[28:29], v[136:137], s[34:35], v[28:29] op_sel_hi:[1,0,1]
	v_pk_fma_f32 v[30:31], v[138:139], s[34:35], v[30:31] op_sel_hi:[1,0,1]
	v_cvt_f32_f16_e32 v136, v198
	v_cvt_f32_f16_sdwa v137, v198 dst_sel:DWORD dst_unused:UNUSED_PAD src0_sel:WORD_1
	v_cvt_f32_f16_e32 v138, v199
	v_cvt_f32_f16_sdwa v139, v199 dst_sel:DWORD dst_unused:UNUSED_PAD src0_sel:WORD_1
	v_pk_fma_f32 v[24:25], v[136:137], s[34:35], v[24:25] op_sel_hi:[1,0,1]
	v_pk_fma_f32 v[26:27], v[138:139], s[34:35], v[26:27] op_sel_hi:[1,0,1]
	v_cvt_pk_f16_f32 v28, v28, v29
	v_cvt_pk_f16_f32 v29, v30, v31
	v_cvt_pk_f16_f32 v30, v24, v25
	v_cvt_pk_f16_f32 v31, v26, v27
	global_store_dwordx4 v132, v[28:31], s[54:55] offset:256
	s_waitcnt vmcnt(15)
	v_cvt_f32_f16_e32 v136, v200
	v_cvt_f32_f16_sdwa v137, v200 dst_sel:DWORD dst_unused:UNUSED_PAD src0_sel:WORD_1
	v_cvt_f32_f16_e32 v138, v201
	v_cvt_f32_f16_sdwa v139, v201 dst_sel:DWORD dst_unused:UNUSED_PAD src0_sel:WORD_1
	v_pk_fma_f32 v[20:21], v[136:137], s[34:35], v[20:21] op_sel_hi:[1,0,1]
	v_pk_fma_f32 v[22:23], v[138:139], s[34:35], v[22:23] op_sel_hi:[1,0,1]
	v_cvt_f32_f16_e32 v136, v202
	v_cvt_f32_f16_sdwa v137, v202 dst_sel:DWORD dst_unused:UNUSED_PAD src0_sel:WORD_1
	v_cvt_f32_f16_e32 v138, v203
	v_cvt_f32_f16_sdwa v139, v203 dst_sel:DWORD dst_unused:UNUSED_PAD src0_sel:WORD_1
	v_pk_fma_f32 v[16:17], v[136:137], s[34:35], v[16:17] op_sel_hi:[1,0,1]
	v_pk_fma_f32 v[18:19], v[138:139], s[34:35], v[18:19] op_sel_hi:[1,0,1]
	v_cvt_pk_f16_f32 v20, v20, v21
	v_cvt_pk_f16_f32 v21, v22, v23
	v_cvt_pk_f16_f32 v22, v16, v17
	v_cvt_pk_f16_f32 v23, v18, v19
	global_store_dwordx4 v133, v[20:23], s[54:55] offset:256
	s_waitcnt vmcnt(15)
	v_cvt_f32_f16_e32 v136, v204
	v_cvt_f32_f16_sdwa v137, v204 dst_sel:DWORD dst_unused:UNUSED_PAD src0_sel:WORD_1
	v_cvt_f32_f16_e32 v138, v205
	v_cvt_f32_f16_sdwa v139, v205 dst_sel:DWORD dst_unused:UNUSED_PAD src0_sel:WORD_1
	v_pk_fma_f32 v[12:13], v[136:137], s[34:35], v[12:13] op_sel_hi:[1,0,1]
	v_pk_fma_f32 v[14:15], v[138:139], s[34:35], v[14:15] op_sel_hi:[1,0,1]
	v_cvt_f32_f16_e32 v136, v206
	v_cvt_f32_f16_sdwa v137, v206 dst_sel:DWORD dst_unused:UNUSED_PAD src0_sel:WORD_1
	v_cvt_f32_f16_e32 v138, v207
	v_cvt_f32_f16_sdwa v139, v207 dst_sel:DWORD dst_unused:UNUSED_PAD src0_sel:WORD_1
	v_pk_fma_f32 v[8:9], v[136:137], s[34:35], v[8:9] op_sel_hi:[1,0,1]
	v_pk_fma_f32 v[10:11], v[138:139], s[34:35], v[10:11] op_sel_hi:[1,0,1]
	v_cvt_pk_f16_f32 v12, v12, v13
	v_cvt_pk_f16_f32 v13, v14, v15
	v_cvt_pk_f16_f32 v14, v8, v9
	v_cvt_pk_f16_f32 v15, v10, v11
	global_store_dwordx4 v134, v[12:15], s[54:55] offset:256
	s_waitcnt vmcnt(15)
	v_cvt_f32_f16_e32 v136, v212
	v_cvt_f32_f16_sdwa v137, v212 dst_sel:DWORD dst_unused:UNUSED_PAD src0_sel:WORD_1
	v_cvt_f32_f16_e32 v138, v213
	v_cvt_f32_f16_sdwa v139, v213 dst_sel:DWORD dst_unused:UNUSED_PAD src0_sel:WORD_1
	v_pk_fma_f32 v[4:5], v[136:137], s[34:35], v[4:5] op_sel_hi:[1,0,1]
	v_pk_fma_f32 v[6:7], v[138:139], s[34:35], v[6:7] op_sel_hi:[1,0,1]
	v_cvt_f32_f16_e32 v136, v214
	v_cvt_f32_f16_sdwa v137, v214 dst_sel:DWORD dst_unused:UNUSED_PAD src0_sel:WORD_1
	v_cvt_f32_f16_e32 v138, v215
	v_cvt_f32_f16_sdwa v139, v215 dst_sel:DWORD dst_unused:UNUSED_PAD src0_sel:WORD_1
	v_pk_fma_f32 v[0:1], v[136:137], s[34:35], v[0:1] op_sel_hi:[1,0,1]
	v_pk_fma_f32 v[2:3], v[138:139], s[34:35], v[2:3] op_sel_hi:[1,0,1]
	v_cvt_pk_f16_f32 v4, v4, v5
	v_cvt_pk_f16_f32 v5, v6, v7
	v_cvt_pk_f16_f32 v6, v0, v1
	v_cvt_pk_f16_f32 v7, v2, v3
	global_store_dwordx4 v135, v[4:7], s[54:55] offset:256
	s_cbranch_vccnz .LBB0_460
	s_andn2_b64 vcc, exec, s[14:15]
	s_cbranch_vccnz .LBB0_459
	s_barrier
	s_branch .LBB0_459

; #define PG8_STAGE(bufoff, gbase, voff) do { _Pragma("unroll") for (int _i = 0; _i < 2; ++_i) glds16_s((gbase), (voff)[_i], ldsb + (unsigned)((bufoff) + _i * 8192)); } while (0)
; #define PG8_LDA(dst, b, h) do { _Pragma("unroll") for (int m = 0; m < 4; ++m) _Pragma("unroll") for (int k = 0; k < 2; ++k) dst[m][k] = *(const LAS h16x8*)(lds + PG8_SA(b, h) + aoff + m * 2048 + k * 1024); } while (0)
; #define PG8_LDB(dst, b, h) do { _Pragma("unroll") for (int n = 0; n < 2; ++n) _Pragma("unroll") for (int k = 0; k < 2; ++k) dst[n][k] = *(const LAS h16x8*)(lds + PG8_SB(b, h) + boff + n * 2048 + k * 1024); } while (0)
; #define PG8_MMA(ai, bj, At, Bt) do { __builtin_amdgcn_s_setprio(1); _Pragma("unroll") for (int m = 0; m < 4; ++m) _Pragma("unroll") for (int n = 0; n < 2; ++n) _Pragma("unroll") for (int k = 0; k < 2; ++k) \
;         acc[ai][bj][m][n] = mma_step<I8>(Bt[n][k], At[m][k], acc[ai][bj][m][n]); __builtin_amdgcn_s_setprio(0); } while (0)
; #define PG8_WAIT_V(n) asm volatile("s_waitcnt vmcnt(" #n ")" ::: "memory")
; #define PG8_WAIT_L(n) asm volatile("s_waitcnt lgkmcnt(" #n ")" ::: "memory")
; #define PG8_BAR __builtin_amdgcn_s_barrier()
; #define PG8_SCHED __builtin_amdgcn_sched_barrier(0)
; template <class Prob, class Epi, bool I8 = false, bool ALIGN_EPI = true, bool SP2 = true>
; __device__ __forceinline__ void gemm_phase(LAS unsigned char* lds, int wave, const Prob& P, const Epi& E) {
;     ...
;             PG8_LDB(B0, 0, 0); PG8_LDB(B1, 0, 1); PG8_SCHED; PG8_LDA(At, 0, 0); PG8_STAGE(PG8_SA(1, 1), a1 + hstepA, voffA);
;             PG8_WAIT_V(8); PG8_WAIT_L(0); PG8_BAR; PG8_MMA(0, 0, At, B0); PG8_MMA(0, 1, At, B1); PG8_BAR; PG8_SCHED;
;             PG8_LDA(At, 0, 1); PG8_STAGE(PG8_SB(0, 0), b2, voffB); PG8_STAGE(PG8_SB(0, 1), b2 + hstepB, voffB); PG8_STAGE(PG8_SA(0, 0), a2, voffA);
;             PG8_WAIT_V(8); PG8_WAIT_L(0); PG8_BAR; PG8_MMA(1, 0, At, B0); PG8_MMA(1, 1, At, B1); PG8_BAR; PG8_SCHED;
.LBB0_863:
	v_add_u32_e32 v140, 0x10000, v146
	ds_read_b128 v[128:131], v140
	ds_read_b128 v[132:135], v140 offset:1024
	ds_read_b128 v[136:139], v140 offset:2048
	ds_read_b128 v[148:151], v140 offset:3072
	v_add_u32_e32 v140, 0x14000, v146
	ds_read_b128 v[152:155], v140
	ds_read_b128 v[156:159], v140 offset:1024
	ds_read_b128 v[160:163], v140 offset:2048
	ds_read_b128 v[164:167], v140 offset:3072
	s_cmp_eq_u32 s1, 28
	s_cselect_b32 s46, s83, s85
	s_cselect_b32 s47, s27, s86
	s_cselect_b32 s44, s84, s87
	s_cselect_b32 s45, s23, s0
	s_add_u32 s42, s46, 0x80
	s_addc_u32 s43, s47, 0
	ds_read_b128 v[168:171], v147
	ds_read_b128 v[172:175], v147 offset:1024
	ds_read_b128 v[176:179], v147 offset:2048
	ds_read_b128 v[180:183], v147 offset:3072
	ds_read_b128 v[184:187], v147 offset:4096
	ds_read_b128 v[188:191], v147 offset:5120
	ds_read_b128 v[192:195], v147 offset:6144
	ds_read_b128 v[196:199], v147 offset:7168
	s_mov_b32 s4, m0
	s_mov_b32 m0, s75
	s_nop 0
	global_load_lds_dwordx4 v142, s[40:41]
	s_mov_b32 m0, s4
	s_nop 0
	s_mov_b32 s4, m0
	s_mov_b32 m0, s79
	s_nop 0
	global_load_lds_dwordx4 v144, s[40:41]
	s_mov_b32 m0, s4
	s_waitcnt vmcnt(8)
	s_waitcnt lgkmcnt(0)
	s_barrier
	s_setprio 1
	s_waitcnt lgkmcnt(7)
	v_mfma_f32_16x16x32_f16 v[124:127], v[128:131], v[168:171], v[124:127]
	v_mfma_f32_16x16x32_f16 v[120:123], v[136:139], v[168:171], v[120:123]
	s_waitcnt lgkmcnt(5)
	v_mfma_f32_16x16x32_f16 v[116:119], v[128:131], v[176:179], v[116:119]
	v_mfma_f32_16x16x32_f16 v[112:115], v[136:139], v[176:179], v[112:115]
	s_waitcnt lgkmcnt(3)
	v_mfma_f32_16x16x32_f16 v[108:111], v[128:131], v[184:187], v[108:111]
	v_mfma_f32_16x16x32_f16 v[104:107], v[136:139], v[184:187], v[104:107]
	s_waitcnt lgkmcnt(1)
	v_mfma_f32_16x16x32_f16 v[100:103], v[128:131], v[192:195], v[100:103]
	v_mfma_f32_16x16x32_f16 v[96:99], v[136:139], v[192:195], v[96:99]
	v_mfma_f32_16x16x32_f16 v[124:127], v[132:135], v[172:175], v[124:127]
	v_mfma_f32_16x16x32_f16 v[120:123], v[148:151], v[172:175], v[120:123]
	v_mfma_f32_16x16x32_f16 v[116:119], v[132:135], v[180:183], v[116:119]
	v_mfma_f32_16x16x32_f16 v[112:115], v[148:151], v[180:183], v[112:115]
	v_mfma_f32_16x16x32_f16 v[108:111], v[132:135], v[188:191], v[108:111]
	v_mfma_f32_16x16x32_f16 v[104:107], v[148:151], v[188:191], v[104:107]
	s_waitcnt lgkmcnt(0)
	v_mfma_f32_16x16x32_f16 v[100:103], v[132:135], v[196:199], v[100:103]
	v_mfma_f32_16x16x32_f16 v[96:99], v[148:151], v[196:199], v[96:99]
	s_setprio 0
	s_setprio 1
	v_mfma_f32_16x16x32_f16 v[64:67], v[152:155], v[168:171], v[64:67]
	v_mfma_f32_16x16x32_f16 v[56:59], v[160:163], v[168:171], v[56:59]
	v_mfma_f32_16x16x32_f16 v[52:55], v[152:155], v[176:179], v[52:55]
	v_mfma_f32_16x16x32_f16 v[48:51], v[160:163], v[176:179], v[48:51]
	v_mfma_f32_16x16x32_f16 v[44:47], v[152:155], v[184:187], v[44:47]
	v_mfma_f32_16x16x32_f16 v[40:43], v[160:163], v[184:187], v[40:43]
	v_mfma_f32_16x16x32_f16 v[36:39], v[152:155], v[192:195], v[36:39]
	v_mfma_f32_16x16x32_f16 v[32:35], v[160:163], v[192:195], v[32:35]
	v_mfma_f32_16x16x32_f16 v[64:67], v[156:159], v[172:175], v[64:67]
	v_mfma_f32_16x16x32_f16 v[56:59], v[164:167], v[172:175], v[56:59]
	v_mfma_f32_16x16x32_f16 v[52:55], v[156:159], v[180:183], v[52:55]
	v_mfma_f32_16x16x32_f16 v[48:51], v[164:167], v[180:183], v[48:51]
	v_mfma_f32_16x16x32_f16 v[44:47], v[156:159], v[188:191], v[44:47]
	v_mfma_f32_16x16x32_f16 v[40:43], v[164:167], v[188:191], v[40:43]
	v_mfma_f32_16x16x32_f16 v[36:39], v[156:159], v[196:199], v[36:39]
	v_mfma_f32_16x16x32_f16 v[32:35], v[164:167], v[196:199], v[32:35]
	s_setprio 0
	s_barrier
	ds_read_b128 v[168:171], v147 offset:16384
	ds_read_b128 v[172:175], v147 offset:17408
	ds_read_b128 v[176:179], v147 offset:18432
	ds_read_b128 v[180:183], v147 offset:19456
	ds_read_b128 v[184:187], v147 offset:20480
	ds_read_b128 v[188:191], v147 offset:21504
	ds_read_b128 v[192:195], v147 offset:22528
	ds_read_b128 v[196:199], v147 offset:23552
	s_mov_b32 s4, m0
	s_mov_b32 m0, s49
	s_nop 0
	global_load_lds_dwordx4 v143, s[44:45]
	s_mov_b32 m0, s4
	s_nop 0
	s_mov_b32 s4, m0
	s_mov_b32 m0, s50
	s_nop 0
	global_load_lds_dwordx4 v145, s[44:45]
	s_mov_b32 m0, s4
	s_add_u32 s4, s44, 0x80000
	s_addc_u32 s5, s45, 0
	s_mov_b32 s6, m0
	s_mov_b32 m0, s51
	s_nop 0
	global_load_lds_dwordx4 v143, s[4:5]
	s_mov_b32 m0, s6
	s_nop 0
	s_mov_b32 s6, m0
	s_mov_b32 m0, s56
	s_nop 0
	global_load_lds_dwordx4 v145, s[4:5]
	s_mov_b32 m0, s6
	s_mov_b32 s4, m0
	s_mov_b32 m0, s48
	s_nop 0
	global_load_lds_dwordx4 v142, s[46:47]
	s_mov_b32 m0, s4
	s_nop 0
	s_mov_b32 s4, m0
	s_mov_b32 m0, s57
	s_nop 0
	global_load_lds_dwordx4 v144, s[46:47]
	s_mov_b32 m0, s4
	s_waitcnt vmcnt(8)
	s_waitcnt lgkmcnt(0)
	s_barrier
; #define PG8_STAGE(bufoff, gbase, voff) do { _Pragma("unroll") for (int _i = 0; _i < 2; ++_i) glds16_s((gbase), (voff)[_i], ldsb + (unsigned)((bufoff) + _i * 8192)); } while (0)
; #define PG8_LDA(dst, b, h) do { _Pragma("unroll") for (int m = 0; m < 4; ++m) _Pragma("unroll") for (int k = 0; k < 2; ++k) dst[m][k] = *(const LAS h16x8*)(lds + PG8_SA(b, h) + aoff + m * 2048 + k * 1024); } while (0)
; #define PG8_LDB(dst, b, h) do { _Pragma("unroll") for (int n = 0; n < 2; ++n) _Pragma("unroll") for (int k = 0; k < 2; ++k) dst[n][k] = *(const LAS h16x8*)(lds + PG8_SB(b, h) + boff + n * 2048 + k * 1024); } while (0)
; #define PG8_MMA(ai, bj, At, Bt) do { __builtin_amdgcn_s_setprio(1); _Pragma("unroll") for (int m = 0; m < 4; ++m) _Pragma("unroll") for (int n = 0; n < 2; ++n) _Pragma("unroll") for (int k = 0; k < 2; ++k) \
;         acc[ai][bj][m][n] = mma_step<I8>(Bt[n][k], At[m][k], acc[ai][bj][m][n]); __builtin_amdgcn_s_setprio(0); } while (0)
; #define PG8_WAIT_V(n) asm volatile("s_waitcnt vmcnt(" #n ")" ::: "memory")
; #define PG8_WAIT_L(n) asm volatile("s_waitcnt lgkmcnt(" #n ")" ::: "memory")
; #define PG8_BAR __builtin_amdgcn_s_barrier()
; #define PG8_SCHED __builtin_amdgcn_sched_barrier(0)
; template <class Prob, class Epi, bool I8 = false, bool ALIGN_EPI = true, bool SP2 = true>
; __device__ __forceinline__ void gemm_phase(LAS unsigned char* lds, int wave, const Prob& P, const Epi& E) {
;     ...
;             PG8_WAIT_V(8); PG8_WAIT_L(0); PG8_BAR; PG8_MMA(1, 0, At, B0); PG8_MMA(1, 1, At, B1); PG8_BAR; PG8_SCHED;
;             PG8_LDB(B0, 1, 0); PG8_LDB(B1, 1, 1); PG8_SCHED; PG8_LDA(At, 1, 0); PG8_STAGE(PG8_SA(0, 1), a2 + hstepA, voffA);
;             PG8_WAIT_V(8); PG8_WAIT_L(0); PG8_BAR; PG8_MMA(0, 0, At, B0); PG8_MMA(0, 1, At, B1); PG8_BAR; PG8_SCHED;
	s_setprio 1
	s_waitcnt lgkmcnt(7)
	v_mfma_f32_16x16x32_f16 v[92:95], v[128:131], v[168:171], v[92:95]
	v_mfma_f32_16x16x32_f16 v[88:91], v[136:139], v[168:171], v[88:91]
	s_waitcnt lgkmcnt(5)
	v_mfma_f32_16x16x32_f16 v[84:87], v[128:131], v[176:179], v[84:87]
	v_mfma_f32_16x16x32_f16 v[80:83], v[136:139], v[176:179], v[80:83]
	s_waitcnt lgkmcnt(3)
	v_mfma_f32_16x16x32_f16 v[76:79], v[128:131], v[184:187], v[76:79]
	v_mfma_f32_16x16x32_f16 v[72:75], v[136:139], v[184:187], v[72:75]
	s_waitcnt lgkmcnt(1)
	v_mfma_f32_16x16x32_f16 v[68:71], v[128:131], v[192:195], v[68:71]
	v_mfma_f32_16x16x32_f16 v[60:63], v[136:139], v[192:195], v[60:63]
	v_mfma_f32_16x16x32_f16 v[92:95], v[132:135], v[172:175], v[92:95]
	v_mfma_f32_16x16x32_f16 v[88:91], v[148:151], v[172:175], v[88:91]
	v_mfma_f32_16x16x32_f16 v[84:87], v[132:135], v[180:183], v[84:87]
	v_mfma_f32_16x16x32_f16 v[80:83], v[148:151], v[180:183], v[80:83]
	v_mfma_f32_16x16x32_f16 v[76:79], v[132:135], v[188:191], v[76:79]
	v_mfma_f32_16x16x32_f16 v[72:75], v[148:151], v[188:191], v[72:75]
	s_waitcnt lgkmcnt(0)
	v_mfma_f32_16x16x32_f16 v[68:71], v[132:135], v[196:199], v[68:71]
	v_mfma_f32_16x16x32_f16 v[60:63], v[148:151], v[196:199], v[60:63]
	s_setprio 0
	s_setprio 1
	v_mfma_f32_16x16x32_f16 v[28:31], v[152:155], v[168:171], v[28:31]
	v_mfma_f32_16x16x32_f16 v[24:27], v[160:163], v[168:171], v[24:27]
	v_mfma_f32_16x16x32_f16 v[20:23], v[152:155], v[176:179], v[20:23]
	v_mfma_f32_16x16x32_f16 v[16:19], v[160:163], v[176:179], v[16:19]
	v_mfma_f32_16x16x32_f16 v[12:15], v[152:155], v[184:187], v[12:15]
	v_mfma_f32_16x16x32_f16 v[8:11], v[160:163], v[184:187], v[8:11]
	v_mfma_f32_16x16x32_f16 v[4:7], v[152:155], v[192:195], v[4:7]
	v_mfma_f32_16x16x32_f16 v[0:3], v[160:163], v[192:195], v[0:3]
	v_mfma_f32_16x16x32_f16 v[28:31], v[156:159], v[172:175], v[28:31]
	v_mfma_f32_16x16x32_f16 v[24:27], v[164:167], v[172:175], v[24:27]
	v_mfma_f32_16x16x32_f16 v[20:23], v[156:159], v[180:183], v[20:23]
	v_mfma_f32_16x16x32_f16 v[16:19], v[164:167], v[180:183], v[16:19]
	v_mfma_f32_16x16x32_f16 v[12:15], v[156:159], v[188:191], v[12:15]
	v_mfma_f32_16x16x32_f16 v[8:11], v[164:167], v[188:191], v[8:11]
	v_mfma_f32_16x16x32_f16 v[4:7], v[156:159], v[196:199], v[4:7]
	v_mfma_f32_16x16x32_f16 v[0:3], v[164:167], v[196:199], v[0:3]
	s_setprio 0
	s_barrier
	v_add_u32_e32 v140, 0x18000, v146
	ds_read_b128 v[128:131], v140
	ds_read_b128 v[132:135], v140 offset:1024
	ds_read_b128 v[136:139], v140 offset:2048
	ds_read_b128 v[148:151], v140 offset:3072
	v_add_u32_e32 v140, 0x1c000, v146
	ds_read_b128 v[152:155], v140
	ds_read_b128 v[156:159], v140 offset:1024
	ds_read_b128 v[160:163], v140 offset:2048
	ds_read_b128 v[164:167], v140 offset:3072
	ds_read_b128 v[168:171], v147 offset:32768
	ds_read_b128 v[172:175], v147 offset:33792
	ds_read_b128 v[176:179], v147 offset:34816
	ds_read_b128 v[180:183], v147 offset:35840
	ds_read_b128 v[184:187], v147 offset:36864
	ds_read_b128 v[188:191], v147 offset:37888
	ds_read_b128 v[192:195], v147 offset:38912
	ds_read_b128 v[196:199], v147 offset:39936
	s_add_u32 s4, s46, 0x80000
	s_addc_u32 s5, s47, 0
	s_mov_b32 s6, m0
	s_mov_b32 m0, s60
	s_nop 0
	global_load_lds_dwordx4 v142, s[4:5]
	s_mov_b32 m0, s6
	s_nop 0
	s_mov_b32 s6, m0
	s_mov_b32 m0, s61
	s_nop 0
	global_load_lds_dwordx4 v144, s[4:5]
	s_mov_b32 m0, s6
	s_waitcnt vmcnt(8)
	s_waitcnt lgkmcnt(0)
	s_barrier
	s_setprio 1
	s_waitcnt lgkmcnt(7)
	v_mfma_f32_16x16x32_f16 v[124:127], v[128:131], v[168:171], v[124:127]
	v_mfma_f32_16x16x32_f16 v[120:123], v[136:139], v[168:171], v[120:123]
	s_waitcnt lgkmcnt(5)
	v_mfma_f32_16x16x32_f16 v[116:119], v[128:131], v[176:179], v[116:119]
	v_mfma_f32_16x16x32_f16 v[112:115], v[136:139], v[176:179], v[112:115]
	s_waitcnt lgkmcnt(3)
	v_mfma_f32_16x16x32_f16 v[108:111], v[128:131], v[184:187], v[108:111]
	v_mfma_f32_16x16x32_f16 v[104:107], v[136:139], v[184:187], v[104:107]
	s_waitcnt lgkmcnt(1)
	v_mfma_f32_16x16x32_f16 v[100:103], v[128:131], v[192:195], v[100:103]
	v_mfma_f32_16x16x32_f16 v[96:99], v[136:139], v[192:195], v[96:99]
	v_mfma_f32_16x16x32_f16 v[124:127], v[132:135], v[172:175], v[124:127]
	v_mfma_f32_16x16x32_f16 v[120:123], v[148:151], v[172:175], v[120:123]
	v_mfma_f32_16x16x32_f16 v[116:119], v[132:135], v[180:183], v[116:119]
	v_mfma_f32_16x16x32_f16 v[112:115], v[148:151], v[180:183], v[112:115]
	v_mfma_f32_16x16x32_f16 v[108:111], v[132:135], v[188:191], v[108:111]
	v_mfma_f32_16x16x32_f16 v[104:107], v[148:151], v[188:191], v[104:107]
	s_waitcnt lgkmcnt(0)
	v_mfma_f32_16x16x32_f16 v[100:103], v[132:135], v[196:199], v[100:103]
	v_mfma_f32_16x16x32_f16 v[96:99], v[148:151], v[196:199], v[96:99]
	s_setprio 0
	s_setprio 1
	v_mfma_f32_16x16x32_f16 v[64:67], v[152:155], v[168:171], v[64:67]
	v_mfma_f32_16x16x32_f16 v[56:59], v[160:163], v[168:171], v[56:59]
	v_mfma_f32_16x16x32_f16 v[52:55], v[152:155], v[176:179], v[52:55]
	v_mfma_f32_16x16x32_f16 v[48:51], v[160:163], v[176:179], v[48:51]
	v_mfma_f32_16x16x32_f16 v[44:47], v[152:155], v[184:187], v[44:47]
	v_mfma_f32_16x16x32_f16 v[40:43], v[160:163], v[184:187], v[40:43]
	v_mfma_f32_16x16x32_f16 v[36:39], v[152:155], v[192:195], v[36:39]
	v_mfma_f32_16x16x32_f16 v[32:35], v[160:163], v[192:195], v[32:35]
	v_mfma_f32_16x16x32_f16 v[64:67], v[156:159], v[172:175], v[64:67]
	v_mfma_f32_16x16x32_f16 v[56:59], v[164:167], v[172:175], v[56:59]
	v_mfma_f32_16x16x32_f16 v[52:55], v[156:159], v[180:183], v[52:55]
	v_mfma_f32_16x16x32_f16 v[48:51], v[164:167], v[180:183], v[48:51]
	v_mfma_f32_16x16x32_f16 v[44:47], v[156:159], v[188:191], v[44:47]
	v_mfma_f32_16x16x32_f16 v[40:43], v[164:167], v[188:191], v[40:43]
	v_mfma_f32_16x16x32_f16 v[36:39], v[156:159], v[196:199], v[36:39]
	v_mfma_f32_16x16x32_f16 v[32:35], v[164:167], v[196:199], v[32:35]
	s_setprio 0
	s_barrier
; template <class Prob, class Epi, bool I8 = false, bool ALIGN_EPI = true, bool SP2 = true>
; __device__ __forceinline__ void gemm_phase(LAS unsigned char* lds, int wave, const Prob& P, const Epi& E) {
;     ...
;             PG8_LDA(At, 1, 1); PG8_STAGE(PG8_SB(1, 0), b3, voffB); PG8_STAGE(PG8_SB(1, 1), b3 + hstepB, voffB); PG8_STAGE(PG8_SA(1, 0), a3, voffA);
;             PG8_WAIT_V(8); PG8_WAIT_L(0); PG8_BAR; PG8_MMA(1, 0, At, B0); PG8_MMA(1, 1, At, B1); PG8_BAR; PG8_SCHED;
;             } else {
;             PG8_LDB(B0, 0, 0); PG8_SCHED; PG8_LDA(At, 0, 0); PG8_STAGE(PG8_SA(1, 1), a1 + hstepA, voffA);
;             PG8_WAIT_L(8); PG8_BAR; PG8_WAIT_L(0); PG8_MMA(0, 0, At, B0); PG8_BAR; PG8_SCHED;
;             PG8_LDB(B1, 0, 1); PG8_STAGE(PG8_SB(0, 0), b2, voffB);
;             PG8_BAR; PG8_WAIT_L(0); PG8_MMA(0, 1, At, B1); PG8_BAR;
;             PG8_LDA(At, 0, 1); PG8_STAGE(PG8_SA(0, 0), a2, voffA);
;             PG8_BAR; PG8_WAIT_L(0); PG8_MMA(1, 0, At, B0); PG8_BAR; PG8_SCHED;
;             PG8_STAGE(PG8_SB(0, 1), b2 + hstepB, voffB);
;             PG8_WAIT_V(6); PG8_BAR; PG8_MMA(1, 1, At, B1); PG8_BAR;
;             PG8_LDB(B0, 1, 0); PG8_SCHED; PG8_LDA(At, 1, 0); PG8_STAGE(PG8_SA(0, 1), a2 + hstepA, voffA);
;             PG8_WAIT_L(8); PG8_BAR; PG8_WAIT_L(0); PG8_MMA(0, 0, At, B0); PG8_BAR; PG8_SCHED;
;             PG8_LDB(B1, 1, 1); PG8_STAGE(PG8_SB(1, 0), b3, voffB);
;             PG8_BAR; PG8_WAIT_L(0); PG8_MMA(0, 1, At, B1); PG8_BAR;
;             PG8_LDA(At, 1, 1); PG8_STAGE(PG8_SA(1, 0), a3, voffA);
;             PG8_BAR; PG8_WAIT_L(0); PG8_MMA(1, 0, At, B0); PG8_BAR; PG8_SCHED;
;             PG8_STAGE(PG8_SB(1, 1), b3 + hstepB, voffB);
;             PG8_WAIT_V(6); PG8_BAR; PG8_MMA(1, 1, At, B1); PG8_BAR;
;             }
;         }
;         if constexpr (ALIGN_EPI) { if (wr == 0) PG8_BAR; }
;     __device__ __forceinline__ void operator()(Acc& acc, const Unit& u, int wr, int wc, int fr, int fq, LAS unsigned char* lds, int tid) const {
;     ...
;             for (int ai = 0; ai < 2; ++ai) {
;                 h16x8 xv[4];
;                 f32x2 st[4]; float rs[4];
; #pragma unroll
;                 for (int m = 0; m < 4; ++m) { const unsigned row = u.pm * 256 + ai * 128 + wr * 64 + m * 16 + fr; xv[m] = *(const h16x8*)(X + (size_t)row * D + colt);
;                     if constexpr (LNX) st[m] = *(const f32x2*)((const char*)stats + (row << 3));
	ds_read_b128 v[168:171], v147 offset:49152
	ds_read_b128 v[172:175], v147 offset:50176
	ds_read_b128 v[176:179], v147 offset:51200
	ds_read_b128 v[180:183], v147 offset:52224
	ds_read_b128 v[184:187], v147 offset:53248
	ds_read_b128 v[188:191], v147 offset:54272
	ds_read_b128 v[192:195], v147 offset:55296
	ds_read_b128 v[196:199], v147 offset:56320
	s_add_u32 s4, s44, 0x80
	s_addc_u32 s5, s45, 0
	s_mov_b32 s6, m0
	s_mov_b32 m0, s64
	s_nop 0
	global_load_lds_dwordx4 v143, s[4:5]
	s_mov_b32 m0, s6
	s_nop 0
	s_mov_b32 s6, m0
	s_mov_b32 m0, s68
	s_nop 0
	global_load_lds_dwordx4 v145, s[4:5]
	s_mov_b32 m0, s6
	s_add_u32 s4, s44, 0x80080
	s_addc_u32 s5, s45, 0
	s_mov_b32 s6, m0
	s_mov_b32 m0, s73
	s_nop 0
	global_load_lds_dwordx4 v143, s[4:5]
	s_mov_b32 m0, s6
	s_nop 0
	s_mov_b32 s6, m0
	s_mov_b32 m0, s74
	s_nop 0
	global_load_lds_dwordx4 v145, s[4:5]
	s_mov_b32 m0, s6
	s_mov_b32 s4, m0
	s_mov_b32 m0, s69
	s_nop 0
	global_load_lds_dwordx4 v142, s[42:43]
	s_mov_b32 m0, s4
	s_nop 0
	s_mov_b32 s4, m0
	s_mov_b32 m0, s72
	s_nop 0
	global_load_lds_dwordx4 v144, s[42:43]
	s_mov_b32 m0, s4
	s_waitcnt vmcnt(8)
	s_waitcnt lgkmcnt(0)
	s_barrier
	s_setprio 1
	s_waitcnt lgkmcnt(7)
	v_mfma_f32_16x16x32_f16 v[92:95], v[128:131], v[168:171], v[92:95]
	v_mfma_f32_16x16x32_f16 v[88:91], v[136:139], v[168:171], v[88:91]
	s_waitcnt lgkmcnt(5)
	v_mfma_f32_16x16x32_f16 v[84:87], v[128:131], v[176:179], v[84:87]
	v_mfma_f32_16x16x32_f16 v[80:83], v[136:139], v[176:179], v[80:83]
	s_waitcnt lgkmcnt(3)
	v_mfma_f32_16x16x32_f16 v[76:79], v[128:131], v[184:187], v[76:79]
	v_mfma_f32_16x16x32_f16 v[72:75], v[136:139], v[184:187], v[72:75]
	s_waitcnt lgkmcnt(1)
	v_mfma_f32_16x16x32_f16 v[68:71], v[128:131], v[192:195], v[68:71]
	v_mfma_f32_16x16x32_f16 v[60:63], v[136:139], v[192:195], v[60:63]
	v_mfma_f32_16x16x32_f16 v[92:95], v[132:135], v[172:175], v[92:95]
	v_mfma_f32_16x16x32_f16 v[88:91], v[148:151], v[172:175], v[88:91]
	v_mfma_f32_16x16x32_f16 v[84:87], v[132:135], v[180:183], v[84:87]
	v_mfma_f32_16x16x32_f16 v[80:83], v[148:151], v[180:183], v[80:83]
	v_mfma_f32_16x16x32_f16 v[76:79], v[132:135], v[188:191], v[76:79]
	v_mfma_f32_16x16x32_f16 v[72:75], v[148:151], v[188:191], v[72:75]
	s_waitcnt lgkmcnt(0)
	v_mfma_f32_16x16x32_f16 v[68:71], v[132:135], v[196:199], v[68:71]
	v_mfma_f32_16x16x32_f16 v[60:63], v[148:151], v[196:199], v[60:63]
	s_setprio 0
	s_setprio 1
	v_mfma_f32_16x16x32_f16 v[28:31], v[152:155], v[168:171], v[28:31]
	v_mfma_f32_16x16x32_f16 v[24:27], v[160:163], v[168:171], v[24:27]
	v_mfma_f32_16x16x32_f16 v[20:23], v[152:155], v[176:179], v[20:23]
	v_mfma_f32_16x16x32_f16 v[16:19], v[160:163], v[176:179], v[16:19]
	v_mfma_f32_16x16x32_f16 v[12:15], v[152:155], v[184:187], v[12:15]
	v_mfma_f32_16x16x32_f16 v[8:11], v[160:163], v[184:187], v[8:11]
	v_mfma_f32_16x16x32_f16 v[4:7], v[152:155], v[192:195], v[4:7]
	v_mfma_f32_16x16x32_f16 v[0:3], v[160:163], v[192:195], v[0:3]
	v_mfma_f32_16x16x32_f16 v[28:31], v[156:159], v[172:175], v[28:31]
	v_mfma_f32_16x16x32_f16 v[24:27], v[164:167], v[172:175], v[24:27]
	v_mfma_f32_16x16x32_f16 v[20:23], v[156:159], v[180:183], v[20:23]
	v_mfma_f32_16x16x32_f16 v[16:19], v[164:167], v[180:183], v[16:19]
	v_mfma_f32_16x16x32_f16 v[12:15], v[156:159], v[188:191], v[12:15]
	v_mfma_f32_16x16x32_f16 v[8:11], v[164:167], v[188:191], v[8:11]
	v_mfma_f32_16x16x32_f16 v[4:7], v[156:159], v[196:199], v[4:7]
	v_mfma_f32_16x16x32_f16 v[0:3], v[164:167], v[196:199], v[0:3]
	s_setprio 0
	s_barrier
	s_add_i32 s1, s1, 2
	s_add_u32 s85, s85, 0x100
	s_addc_u32 s86, s86, 0
	s_add_u32 s87, s87, 0x100
	s_addc_u32 s0, s0, 0
	s_add_u32 s40, s40, 0x100
	s_addc_u32 s41, s41, 0
	s_cmp_gt_u32 s1, 29
	s_cbranch_scc0 .LBB0_863
	v_mbcnt_lo_u32_b32 v128, -1, 0
	v_mbcnt_hi_u32_b32 v128, -1, v128
	s_lshl_b32 s0, s82, 8
	s_lshl_b32 s1, s81, 8
	v_lshrrev_b32_e32 v129, 1, v128
	s_add_i32 s1, s1, s62
	v_and_or_b32 v129, v129, 24, s0
	v_and_or_b32 v130, v128, 15, s1
	v_or_b32_e32 v129, s63, v129
	v_lshlrev_b32_e32 v130, 12, v130
	v_lshl_add_u32 v128, v129, 1, v130
	v_add_u32_e32 v129, 0x10000, v128
	v_add_u32_e32 v130, 0x20000, v128
	v_add_u32_e32 v131, 0x30000, v128
	v_add_u32_e32 v132, 0x80000, v128
	v_add_u32_e32 v133, 0x90000, v128
	v_add_u32_e32 v134, 0xa0000, v128
	v_add_u32_e32 v135, 0xb0000, v128
	global_load_dwordx4 v[148:151], v128, s[54:55]
	global_load_dwordx4 v[152:155], v129, s[54:55]
	global_load_dwordx4 v[156:159], v130, s[54:55]
	global_load_dwordx4 v[160:163], v131, s[54:55]
	global_load_dwordx4 v[164:167], v132, s[54:55]
	global_load_dwordx4 v[168:171], v133, s[54:55]
	global_load_dwordx4 v[172:175], v134, s[54:55]
	global_load_dwordx4 v[176:179], v135, s[54:55]
	global_load_dwordx4 v[180:183], v128, s[54:55] offset:256
	global_load_dwordx4 v[184:187], v129, s[54:55] offset:256
	global_load_dwordx4 v[188:191], v130, s[54:55] offset:256
	global_load_dwordx4 v[192:195], v131, s[54:55] offset:256
	global_load_dwordx4 v[196:199], v132, s[54:55] offset:256
	global_load_dwordx4 v[200:203], v133, s[54:55] offset:256
	global_load_dwordx4 v[204:207], v134, s[54:55] offset:256
	global_load_dwordx4 v[212:215], v135, s[54:55] offset:256
	s_and_b64 vcc, exec, s[16:17]
	s_cbranch_vccz .LBB0_866
	s_barrier
